# P0 weight transpose: all 32 loads of an item in flight (4-trip load loop unrolled, suffix vmcnt waits)
# baseline (speedup 1.0000x reference)
; #define LAS __attribute__((address_space(3)))
; #define LDS_WAIT() asm volatile("s_waitcnt lgkmcnt(0)" ::: "memory")
; __device__ __forceinline__ void p0_transpose_item(const float* W, int K, int N, bfu* WT, int drow0, LAS float* scr, int k0, int n0, int lane, const float* gk) {
; #pragma unroll 8
;     for (int i = 0; i < 32; ++i) { const int kk = 2 * i + (lane >> 5); scr[kk * 33 + (lane & 31)] = __builtin_nontemporal_load(W + (size_t)(k0 + kk) * N + n0 + (lane & 31)); }
;     LDS_WAIT(); asm volatile("" ::: "memory");
.LBB0_28:
	v_lshl_add_u64 v[54:55], v[20:21], 0, s[26:27]
	v_lshl_add_u64 v[56:57], v[18:19], 0, s[26:27]
	v_lshl_add_u64 v[58:59], v[16:17], 0, s[26:27]
	v_lshl_add_u64 v[60:61], v[14:15], 0, s[26:27]
	v_lshl_add_u64 v[62:63], v[6:7], 0, s[26:27]
	v_lshl_add_u64 v[64:65], v[4:5], 0, s[26:27]
	v_lshl_add_u64 v[66:67], v[2:3], 0, s[26:27]
	v_lshl_add_u64 v[68:69], v[0:1], 0, s[26:27]
	global_load_dword v70, v[54:55], off nt
	global_load_dword v71, v[56:57], off nt
	global_load_dword v72, v[58:59], off nt
	global_load_dword v73, v[60:61], off nt
	global_load_dword v74, v[62:63], off nt
	global_load_dword v75, v[64:65], off nt
	global_load_dword v76, v[66:67], off nt
	global_load_dword v77, v[68:69], off nt
	s_add_u32 s26, s26, 0x20000
	s_addc_u32 s27, s27, 0
	v_lshl_add_u64 v[54:55], v[20:21], 0, s[26:27]
	v_lshl_add_u64 v[56:57], v[18:19], 0, s[26:27]
	v_lshl_add_u64 v[58:59], v[16:17], 0, s[26:27]
	v_lshl_add_u64 v[60:61], v[14:15], 0, s[26:27]
	v_lshl_add_u64 v[62:63], v[6:7], 0, s[26:27]
	v_lshl_add_u64 v[64:65], v[4:5], 0, s[26:27]
	v_lshl_add_u64 v[66:67], v[2:3], 0, s[26:27]
	v_lshl_add_u64 v[68:69], v[0:1], 0, s[26:27]
	global_load_dword v78, v[54:55], off nt
	global_load_dword v79, v[56:57], off nt
	global_load_dword v80, v[58:59], off nt
	global_load_dword v81, v[60:61], off nt
	global_load_dword v82, v[62:63], off nt
	global_load_dword v83, v[64:65], off nt
	global_load_dword v84, v[66:67], off nt
	global_load_dword v85, v[68:69], off nt
	s_add_u32 s26, s26, 0x20000
	s_addc_u32 s27, s27, 0
	v_lshl_add_u64 v[54:55], v[20:21], 0, s[26:27]
	v_lshl_add_u64 v[56:57], v[18:19], 0, s[26:27]
	v_lshl_add_u64 v[58:59], v[16:17], 0, s[26:27]
	v_lshl_add_u64 v[60:61], v[14:15], 0, s[26:27]
	v_lshl_add_u64 v[62:63], v[6:7], 0, s[26:27]
	v_lshl_add_u64 v[64:65], v[4:5], 0, s[26:27]
	v_lshl_add_u64 v[66:67], v[2:3], 0, s[26:27]
	v_lshl_add_u64 v[68:69], v[0:1], 0, s[26:27]
	global_load_dword v86, v[54:55], off nt
	global_load_dword v87, v[56:57], off nt
	global_load_dword v88, v[58:59], off nt
	global_load_dword v89, v[60:61], off nt
	global_load_dword v90, v[62:63], off nt
	global_load_dword v91, v[64:65], off nt
	global_load_dword v92, v[66:67], off nt
	global_load_dword v93, v[68:69], off nt
	s_add_u32 s26, s26, 0x20000
	s_addc_u32 s27, s27, 0
	v_lshl_add_u64 v[54:55], v[20:21], 0, s[26:27]
	v_lshl_add_u64 v[56:57], v[18:19], 0, s[26:27]
	v_lshl_add_u64 v[58:59], v[16:17], 0, s[26:27]
	v_lshl_add_u64 v[60:61], v[14:15], 0, s[26:27]
	v_lshl_add_u64 v[62:63], v[6:7], 0, s[26:27]
	v_lshl_add_u64 v[64:65], v[4:5], 0, s[26:27]
	v_lshl_add_u64 v[66:67], v[2:3], 0, s[26:27]
	v_lshl_add_u64 v[68:69], v[0:1], 0, s[26:27]
	global_load_dword v94, v[54:55], off nt
	global_load_dword v95, v[56:57], off nt
	global_load_dword v96, v[58:59], off nt
	global_load_dword v97, v[60:61], off nt
	global_load_dword v98, v[62:63], off nt
	global_load_dword v99, v[64:65], off nt
	global_load_dword v100, v[66:67], off nt
	global_load_dword v101, v[68:69], off nt
	s_add_u32 s26, s26, 0x20000
	s_addc_u32 s27, s27, 0
	v_add_u32_e32 v54, 0x400, v10
	s_waitcnt vmcnt(30)
	ds_write2_b32 v10, v70, v71 offset1:66
	s_waitcnt vmcnt(28)
	ds_write2_b32 v10, v72, v73 offset0:132 offset1:198
	s_waitcnt vmcnt(26)
	ds_write2_b32 v54, v74, v75 offset0:8 offset1:74
	s_waitcnt vmcnt(24)
	ds_write2_b32 v54, v76, v77 offset0:140 offset1:206
	v_add_u32_e32 v10, 0x840, v10
	v_add_u32_e32 v54, 0x400, v10
	s_waitcnt vmcnt(22)
	ds_write2_b32 v10, v78, v79 offset1:66
	s_waitcnt vmcnt(20)
	ds_write2_b32 v10, v80, v81 offset0:132 offset1:198
	s_waitcnt vmcnt(18)
; #define LAS __attribute__((address_space(3)))
; #define LDS_WAIT() asm volatile("s_waitcnt lgkmcnt(0)" ::: "memory")
; __device__ __forceinline__ unsigned pk2(float lo, float hi) { return pg8::cvt_pk_bf16(lo, hi); }
; __device__ __forceinline__ void p0_transpose_item(const float* W, int K, int N, bfu* WT, int drow0, LAS float* scr, int k0, int n0, int lane, const float* gk) {
;     ...
;     for (int i = 0; i < 32; ++i) { const int kk = 2 * i + (lane >> 5); scr[kk * 33 + (lane & 31)] = __builtin_nontemporal_load(W + (size_t)(k0 + kk) * N + n0 + (lane & 31)); }
;     LDS_WAIT(); asm volatile("" ::: "memory");
;     const int c = lane & 7;
;     f32x4 ga = (f32x4){1.f, 1.f, 1.f, 1.f}, gb = ga;
;     if (gk) { ga = *(const f32x4*)(gk + k0 + 8 * c); gb = *(const f32x4*)(gk + k0 + 8 * c + 4); }
; #pragma unroll
;     for (int j = 0; j < 4; ++j) { const int n = (lane >> 3) + 8 * j; const LAS float* s = scr + (8 * c) * 33 + n;
;         v4u o; o.x = pk2(s[0 * 33] * ga.x, s[1 * 33] * ga.y); o.y = pk2(s[2 * 33] * ga.z, s[3 * 33] * ga.w); o.z = pk2(s[4 * 33] * gb.x, s[5 * 33] * gb.y); o.w = pk2(s[6 * 33] * gb.z, s[7 * 33] * gb.w);
;         *(v4u*)(WT + (size_t)(drow0 + n) * K + k0 + 8 * c) = o; }
;     LDS_WAIT(); asm volatile("" ::: "memory");
	ds_write2_b32 v54, v82, v83 offset0:8 offset1:74
	s_waitcnt vmcnt(16)
	ds_write2_b32 v54, v84, v85 offset0:140 offset1:206
	v_add_u32_e32 v10, 0x840, v10
	v_add_u32_e32 v54, 0x400, v10
	s_waitcnt vmcnt(14)
	ds_write2_b32 v10, v86, v87 offset1:66
	s_waitcnt vmcnt(12)
	ds_write2_b32 v10, v88, v89 offset0:132 offset1:198
	s_waitcnt vmcnt(10)
	ds_write2_b32 v54, v90, v91 offset0:8 offset1:74
	s_waitcnt vmcnt(8)
	ds_write2_b32 v54, v92, v93 offset0:140 offset1:206
	v_add_u32_e32 v10, 0x840, v10
	v_add_u32_e32 v54, 0x400, v10
	s_waitcnt vmcnt(6)
	ds_write2_b32 v10, v94, v95 offset1:66
	s_waitcnt vmcnt(4)
	ds_write2_b32 v10, v96, v97 offset0:132 offset1:198
	s_waitcnt vmcnt(2)
	ds_write2_b32 v54, v98, v99 offset0:8 offset1:74
	s_waitcnt vmcnt(0)
	ds_write2_b32 v54, v100, v101 offset0:140 offset1:206
	v_add_u32_e32 v10, 0x840, v10
	s_and_b32 s4, s30, 0x7fffffc0
	s_lshl_b32 s27, s38, 5
	s_addk_i32 s4, 0xb300
	s_mul_i32 s26, s22, 0x1600000
	s_and_b32 s27, s27, 0x7e0
	s_mul_hi_i32 s23, s22, 0x1600000
	s_add_u32 s26, s24, s26
	s_addc_u32 s23, s25, s23
	s_waitcnt lgkmcnt(0)
	s_lshl_b64 s[24:25], s[4:5], 1
	s_add_u32 s24, s26, s24
	s_addc_u32 s25, s23, s25
	v_lshlrev_b32_e32 v10, 1, v8
	ds_read2_b32 v[4:5], v25 offset0:33 offset1:41
	ds_read2_b32 v[6:7], v25 offset1:8
	ds_read2_b32 v[14:15], v25 offset0:66 offset1:74
	ds_read2_b32 v[16:17], v25 offset0:99 offset1:107
	ds_read2_b32 v[18:19], v25 offset0:132 offset1:140
	ds_read2_b32 v[20:21], v25 offset0:165 offset1:173
	ds_read2_b32 v[54:55], v25 offset0:198 offset1:206
	ds_read2_b32 v[56:57], v25 offset0:231 offset1:239
	v_lshl_add_u64 v[0:1], s[24:25], 0, v[10:11]
	v_lshl_add_u64 v[58:59], v[0:1], 0, s[6:7]
	s_waitcnt lgkmcnt(6)
	v_cvt_pk_bf16_f32 v0, v6, v4
	v_or_b32_e32 v4, s27, v24
	v_mul_u32_u24_e32 v4, 0x1600, v4
	v_lshlrev_b32_e32 v10, 1, v4
	s_waitcnt lgkmcnt(4)
	v_cvt_pk_bf16_f32 v1, v14, v16
	s_waitcnt lgkmcnt(2)
	v_cvt_pk_bf16_f32 v2, v18, v20
	s_waitcnt lgkmcnt(0)
	v_cvt_pk_bf16_f32 v3, v54, v56
	v_lshl_add_u64 v[60:61], v[58:59], 0, v[10:11]
	v_or_b32_e32 v4, s27, v26
	global_store_dwordx4 v[60:61], v[0:3], off
	v_mul_u32_u24_e32 v4, 0x1600, v4
	v_lshlrev_b32_e32 v10, 1, v4
	v_cvt_pk_bf16_f32 v0, v7, v5
	v_cvt_pk_bf16_f32 v1, v15, v17
	v_cvt_pk_bf16_f32 v2, v19, v21
	v_cvt_pk_bf16_f32 v3, v55, v57
	ds_read2_b32 v[6:7], v25 offset0:16 offset1:24
	ds_read2_b32 v[14:15], v25 offset0:49 offset1:57
	ds_read2_b32 v[16:17], v25 offset0:82 offset1:90
	ds_read2_b32 v[18:19], v25 offset0:115 offset1:123
	ds_read2_b32 v[20:21], v25 offset0:148 offset1:156
	ds_read2_b32 v[54:55], v25 offset0:181 offset1:189
	ds_read2_b32 v[56:57], v25 offset0:214 offset1:222
	ds_read2_b32 v[60:61], v25 offset0:247 offset1:255
	v_lshl_add_u64 v[4:5], v[58:59], 0, v[10:11]
	global_store_dwordx4 v[4:5], v[0:3], off
	v_or_b32_e32 v4, s27, v27
	v_mul_u32_u24_e32 v4, 0x1600, v4
	v_lshlrev_b32_e32 v10, 1, v4
	s_waitcnt lgkmcnt(6)
	v_cvt_pk_bf16_f32 v0, v6, v14
	s_waitcnt lgkmcnt(4)
	v_cvt_pk_bf16_f32 v1, v16, v18
	s_waitcnt lgkmcnt(2)
	v_cvt_pk_bf16_f32 v2, v20, v54
	s_waitcnt lgkmcnt(0)
	v_cvt_pk_bf16_f32 v3, v56, v60
	v_lshl_add_u64 v[4:5], v[58:59], 0, v[10:11]
	global_store_dwordx4 v[4:5], v[0:3], off
	v_or_b32_e32 v4, s27, v28
	v_mul_u32_u24_e32 v4, 0x1600, v4
	v_lshlrev_b32_e32 v10, 1, v4
	v_cvt_pk_bf16_f32 v0, v7, v15
	v_cvt_pk_bf16_f32 v1, v17, v19
	v_cvt_pk_bf16_f32 v2, v21, v55
	v_cvt_pk_bf16_f32 v3, v57, v61
	v_lshl_add_u64 v[4:5], v[58:59], 0, v[10:11]
	global_store_dwordx4 v[4:5], v[0:3], off
	s_waitcnt lgkmcnt(0)
	s_mov_b64 s[24:25], 0

; #define LAS __attribute__((address_space(3)))
; #define LDS_WAIT() asm volatile("s_waitcnt lgkmcnt(0)" ::: "memory")
; __device__ __forceinline__ void p0_transpose_item(const float* W, int K, int N, bfu* WT, int drow0, LAS float* scr, int k0, int n0, int lane, const float* gk) {
; #pragma unroll 8
;     for (int i = 0; i < 32; ++i) { const int kk = 2 * i + (lane >> 5); scr[kk * 33 + (lane & 31)] = __builtin_nontemporal_load(W + (size_t)(k0 + kk) * N + n0 + (lane & 31)); }
;     LDS_WAIT(); asm volatile("" ::: "memory");
;     const int c = lane & 7;
;     f32x4 ga = (f32x4){1.f, 1.f, 1.f, 1.f}, gb = ga;
;     if (gk) { ga = *(const f32x4*)(gk + k0 + 8 * c); gb = *(const f32x4*)(gk + k0 + 8 * c + 4); }
.LBB0_32:
	v_lshl_add_u64 v[54:55], v[20:21], 0, s[28:29]
	v_lshl_add_u64 v[56:57], v[18:19], 0, s[28:29]
	v_lshl_add_u64 v[58:59], v[16:17], 0, s[28:29]
	v_lshl_add_u64 v[60:61], v[14:15], 0, s[28:29]
	v_lshl_add_u64 v[62:63], v[6:7], 0, s[28:29]
	v_lshl_add_u64 v[64:65], v[4:5], 0, s[28:29]
	v_lshl_add_u64 v[66:67], v[2:3], 0, s[28:29]
	v_lshl_add_u64 v[68:69], v[0:1], 0, s[28:29]
	global_load_dword v70, v[54:55], off nt
	global_load_dword v71, v[56:57], off nt
	global_load_dword v72, v[58:59], off nt
	global_load_dword v73, v[60:61], off nt
	global_load_dword v74, v[62:63], off nt
	global_load_dword v75, v[64:65], off nt
	global_load_dword v76, v[66:67], off nt
	global_load_dword v77, v[68:69], off nt
	s_add_u32 s28, s28, 0x58000
	s_addc_u32 s29, s29, 0
	v_lshl_add_u64 v[54:55], v[20:21], 0, s[28:29]
	v_lshl_add_u64 v[56:57], v[18:19], 0, s[28:29]
	v_lshl_add_u64 v[58:59], v[16:17], 0, s[28:29]
	v_lshl_add_u64 v[60:61], v[14:15], 0, s[28:29]
	v_lshl_add_u64 v[62:63], v[6:7], 0, s[28:29]
	v_lshl_add_u64 v[64:65], v[4:5], 0, s[28:29]
	v_lshl_add_u64 v[66:67], v[2:3], 0, s[28:29]
	v_lshl_add_u64 v[68:69], v[0:1], 0, s[28:29]
	global_load_dword v78, v[54:55], off nt
	global_load_dword v79, v[56:57], off nt
	global_load_dword v80, v[58:59], off nt
	global_load_dword v81, v[60:61], off nt
	global_load_dword v82, v[62:63], off nt
	global_load_dword v83, v[64:65], off nt
	global_load_dword v84, v[66:67], off nt
	global_load_dword v85, v[68:69], off nt
	s_add_u32 s28, s28, 0x58000
	s_addc_u32 s29, s29, 0
	v_lshl_add_u64 v[54:55], v[20:21], 0, s[28:29]
	v_lshl_add_u64 v[56:57], v[18:19], 0, s[28:29]
	v_lshl_add_u64 v[58:59], v[16:17], 0, s[28:29]
	v_lshl_add_u64 v[60:61], v[14:15], 0, s[28:29]
	v_lshl_add_u64 v[62:63], v[6:7], 0, s[28:29]
	v_lshl_add_u64 v[64:65], v[4:5], 0, s[28:29]
	v_lshl_add_u64 v[66:67], v[2:3], 0, s[28:29]
	v_lshl_add_u64 v[68:69], v[0:1], 0, s[28:29]
	global_load_dword v86, v[54:55], off nt
	global_load_dword v87, v[56:57], off nt
	global_load_dword v88, v[58:59], off nt
	global_load_dword v89, v[60:61], off nt
	global_load_dword v90, v[62:63], off nt
	global_load_dword v91, v[64:65], off nt
	global_load_dword v92, v[66:67], off nt
	global_load_dword v93, v[68:69], off nt
	s_add_u32 s28, s28, 0x58000
	s_addc_u32 s29, s29, 0
	v_lshl_add_u64 v[54:55], v[20:21], 0, s[28:29]
	v_lshl_add_u64 v[56:57], v[18:19], 0, s[28:29]
	v_lshl_add_u64 v[58:59], v[16:17], 0, s[28:29]
	v_lshl_add_u64 v[60:61], v[14:15], 0, s[28:29]
	v_lshl_add_u64 v[62:63], v[6:7], 0, s[28:29]
	v_lshl_add_u64 v[64:65], v[4:5], 0, s[28:29]
	v_lshl_add_u64 v[66:67], v[2:3], 0, s[28:29]
	v_lshl_add_u64 v[68:69], v[0:1], 0, s[28:29]
	global_load_dword v94, v[54:55], off nt
	global_load_dword v95, v[56:57], off nt
	global_load_dword v96, v[58:59], off nt
	global_load_dword v97, v[60:61], off nt
	global_load_dword v98, v[62:63], off nt
	global_load_dword v99, v[64:65], off nt
	global_load_dword v100, v[66:67], off nt
	global_load_dword v101, v[68:69], off nt
	s_add_u32 s28, s28, 0x58000
	s_addc_u32 s29, s29, 0
	v_add_u32_e32 v54, 0x400, v10
	s_waitcnt vmcnt(30)
	ds_write2_b32 v10, v70, v71 offset1:66
	s_waitcnt vmcnt(28)
	ds_write2_b32 v10, v72, v73 offset0:132 offset1:198
	s_waitcnt vmcnt(26)
	ds_write2_b32 v54, v74, v75 offset0:8 offset1:74
	s_waitcnt vmcnt(24)
	ds_write2_b32 v54, v76, v77 offset0:140 offset1:206
	v_add_u32_e32 v10, 0x840, v10
	v_add_u32_e32 v54, 0x400, v10
	s_waitcnt vmcnt(22)
	ds_write2_b32 v10, v78, v79 offset1:66
	s_waitcnt vmcnt(20)
	ds_write2_b32 v10, v80, v81 offset0:132 offset1:198
	s_waitcnt vmcnt(18)
	ds_write2_b32 v54, v82, v83 offset0:8 offset1:74
	s_waitcnt vmcnt(16)
	ds_write2_b32 v54, v84, v85 offset0:140 offset1:206
	v_add_u32_e32 v10, 0x840, v10
	v_add_u32_e32 v54, 0x400, v10
	s_waitcnt vmcnt(14)
	ds_write2_b32 v10, v86, v87 offset1:66
	s_waitcnt vmcnt(12)
	ds_write2_b32 v10, v88, v89 offset0:132 offset1:198
	s_waitcnt vmcnt(10)
	ds_write2_b32 v54, v90, v91 offset0:8 offset1:74
	s_waitcnt vmcnt(8)
	ds_write2_b32 v54, v92, v93 offset0:140 offset1:206
	v_add_u32_e32 v10, 0x840, v10
	v_add_u32_e32 v54, 0x400, v10
	s_waitcnt vmcnt(6)
	ds_write2_b32 v10, v94, v95 offset1:66
	s_waitcnt vmcnt(4)
	ds_write2_b32 v10, v96, v97 offset0:132 offset1:198
	s_waitcnt vmcnt(2)
	ds_write2_b32 v54, v98, v99 offset0:8 offset1:74
	s_waitcnt vmcnt(0)
	ds_write2_b32 v54, v100, v101 offset0:140 offset1:206
	v_add_u32_e32 v10, 0x840, v10
	s_waitcnt lgkmcnt(0)
	s_and_b32 s28, s39, 0xffff
	s_waitcnt lgkmcnt(0)
	s_cmp_lg_u64 s[26:27], 0
	s_cbranch_scc0 .LBB0_58
	s_lshl_b32 s40, s22, 11
	s_ashr_i32 s41, s40, 31
	s_lshl_b64 s[40:41], s[40:41], 2
	s_add_u32 s26, s26, s40
	s_addc_u32 s27, s27, s41
	s_lshl_b32 s29, s28, 2
	s_add_u32 s26, s26, s29
	s_addc_u32 s27, s27, 0
	v_lshlrev_b32_e32 v10, 2, v8
	global_load_dwordx4 v[0:3], v10, s[26:27] offset:16
	global_load_dwordx4 v[4:7], v10, s[26:27]
	s_cbranch_execnz .LBB0_36

; #define LAS __attribute__((address_space(3)))
; #define LDS_WAIT() asm volatile("s_waitcnt lgkmcnt(0)" ::: "memory")
; __device__ __forceinline__ unsigned pk2(float lo, float hi) { return pg8::cvt_pk_bf16(lo, hi); }
; __device__ __forceinline__ void p0_transpose_item(const float* W, int K, int N, bfu* WT, int drow0, LAS float* scr, int k0, int n0, int lane, const float* gk) {
; #pragma unroll 8
;     for (int i = 0; i < 32; ++i) { const int kk = 2 * i + (lane >> 5); scr[kk * 33 + (lane & 31)] = __builtin_nontemporal_load(W + (size_t)(k0 + kk) * N + n0 + (lane & 31)); }
;     LDS_WAIT(); asm volatile("" ::: "memory");
;     const int c = lane & 7;
;     f32x4 ga = (f32x4){1.f, 1.f, 1.f, 1.f}, gb = ga;
;     if (gk) { ga = *(const f32x4*)(gk + k0 + 8 * c); gb = *(const f32x4*)(gk + k0 + 8 * c + 4); }
; #pragma unroll
;     for (int j = 0; j < 4; ++j) { const int n = (lane >> 3) + 8 * j; const LAS float* s = scr + (8 * c) * 33 + n;
;         v4u o; o.x = pk2(s[0 * 33] * ga.x, s[1 * 33] * ga.y); o.y = pk2(s[2 * 33] * ga.z, s[3 * 33] * ga.w); o.z = pk2(s[4 * 33] * gb.x, s[5 * 33] * gb.y); o.w = pk2(s[6 * 33] * gb.z, s[7 * 33] * gb.w);
;         *(v4u*)(WT + (size_t)(drow0 + n) * K + k0 + 8 * c) = o; }
;     LDS_WAIT(); asm volatile("" ::: "memory");
.LBB0_48:
	v_lshl_add_u64 v[54:55], v[20:21], 0, s[26:27]
	v_lshl_add_u64 v[56:57], v[18:19], 0, s[26:27]
	v_lshl_add_u64 v[58:59], v[16:17], 0, s[26:27]
	v_lshl_add_u64 v[60:61], v[14:15], 0, s[26:27]
	v_lshl_add_u64 v[62:63], v[6:7], 0, s[26:27]
	v_lshl_add_u64 v[64:65], v[4:5], 0, s[26:27]
	v_lshl_add_u64 v[66:67], v[2:3], 0, s[26:27]
	v_lshl_add_u64 v[68:69], v[0:1], 0, s[26:27]
	global_load_dword v70, v[54:55], off nt
	global_load_dword v71, v[56:57], off nt
	global_load_dword v72, v[58:59], off nt
	global_load_dword v73, v[60:61], off nt
	global_load_dword v74, v[62:63], off nt
	global_load_dword v75, v[64:65], off nt
	global_load_dword v76, v[66:67], off nt
	global_load_dword v77, v[68:69], off nt
	s_add_u32 s26, s26, 0x20000
	s_addc_u32 s27, s27, 0
	v_lshl_add_u64 v[54:55], v[20:21], 0, s[26:27]
	v_lshl_add_u64 v[56:57], v[18:19], 0, s[26:27]
	v_lshl_add_u64 v[58:59], v[16:17], 0, s[26:27]
	v_lshl_add_u64 v[60:61], v[14:15], 0, s[26:27]
	v_lshl_add_u64 v[62:63], v[6:7], 0, s[26:27]
	v_lshl_add_u64 v[64:65], v[4:5], 0, s[26:27]
	v_lshl_add_u64 v[66:67], v[2:3], 0, s[26:27]
	v_lshl_add_u64 v[68:69], v[0:1], 0, s[26:27]
	global_load_dword v78, v[54:55], off nt
	global_load_dword v79, v[56:57], off nt
	global_load_dword v80, v[58:59], off nt
	global_load_dword v81, v[60:61], off nt
	global_load_dword v82, v[62:63], off nt
	global_load_dword v83, v[64:65], off nt
	global_load_dword v84, v[66:67], off nt
	global_load_dword v85, v[68:69], off nt
	s_add_u32 s26, s26, 0x20000
	s_addc_u32 s27, s27, 0
	v_lshl_add_u64 v[54:55], v[20:21], 0, s[26:27]
	v_lshl_add_u64 v[56:57], v[18:19], 0, s[26:27]
	v_lshl_add_u64 v[58:59], v[16:17], 0, s[26:27]
	v_lshl_add_u64 v[60:61], v[14:15], 0, s[26:27]
	v_lshl_add_u64 v[62:63], v[6:7], 0, s[26:27]
	v_lshl_add_u64 v[64:65], v[4:5], 0, s[26:27]
	v_lshl_add_u64 v[66:67], v[2:3], 0, s[26:27]
	v_lshl_add_u64 v[68:69], v[0:1], 0, s[26:27]
	global_load_dword v86, v[54:55], off nt
	global_load_dword v87, v[56:57], off nt
	global_load_dword v88, v[58:59], off nt
	global_load_dword v89, v[60:61], off nt
	global_load_dword v90, v[62:63], off nt
	global_load_dword v91, v[64:65], off nt
	global_load_dword v92, v[66:67], off nt
	global_load_dword v93, v[68:69], off nt
	s_add_u32 s26, s26, 0x20000
	s_addc_u32 s27, s27, 0
	v_lshl_add_u64 v[54:55], v[20:21], 0, s[26:27]
	v_lshl_add_u64 v[56:57], v[18:19], 0, s[26:27]
	v_lshl_add_u64 v[58:59], v[16:17], 0, s[26:27]
	v_lshl_add_u64 v[60:61], v[14:15], 0, s[26:27]
	v_lshl_add_u64 v[62:63], v[6:7], 0, s[26:27]
	v_lshl_add_u64 v[64:65], v[4:5], 0, s[26:27]
	v_lshl_add_u64 v[66:67], v[2:3], 0, s[26:27]
	v_lshl_add_u64 v[68:69], v[0:1], 0, s[26:27]
	global_load_dword v94, v[54:55], off nt
	global_load_dword v95, v[56:57], off nt
	global_load_dword v96, v[58:59], off nt
	global_load_dword v97, v[60:61], off nt
	global_load_dword v98, v[62:63], off nt
	global_load_dword v99, v[64:65], off nt
	global_load_dword v100, v[66:67], off nt
	global_load_dword v101, v[68:69], off nt
	s_add_u32 s26, s26, 0x20000
	s_addc_u32 s27, s27, 0
	v_add_u32_e32 v54, 0x400, v10
	s_waitcnt vmcnt(30)
	ds_write2_b32 v10, v70, v71 offset1:66
	s_waitcnt vmcnt(28)
	ds_write2_b32 v10, v72, v73 offset0:132 offset1:198
	s_waitcnt vmcnt(26)
	ds_write2_b32 v54, v74, v75 offset0:8 offset1:74
	s_waitcnt vmcnt(24)
	ds_write2_b32 v54, v76, v77 offset0:140 offset1:206
	v_add_u32_e32 v10, 0x840, v10
	v_add_u32_e32 v54, 0x400, v10
	s_waitcnt vmcnt(22)
	ds_write2_b32 v10, v78, v79 offset1:66
	s_waitcnt vmcnt(20)
	ds_write2_b32 v10, v80, v81 offset0:132 offset1:198
	s_waitcnt vmcnt(18)
	ds_write2_b32 v54, v82, v83 offset0:8 offset1:74
	s_waitcnt vmcnt(16)
	ds_write2_b32 v54, v84, v85 offset0:140 offset1:206
	v_add_u32_e32 v10, 0x840, v10
	v_add_u32_e32 v54, 0x400, v10
	s_waitcnt vmcnt(14)
	ds_write2_b32 v10, v86, v87 offset1:66
	s_waitcnt vmcnt(12)
	ds_write2_b32 v10, v88, v89 offset0:132 offset1:198
	s_waitcnt vmcnt(10)
	ds_write2_b32 v54, v90, v91 offset0:8 offset1:74
	s_waitcnt vmcnt(8)
	ds_write2_b32 v54, v92, v93 offset0:140 offset1:206
	v_add_u32_e32 v10, 0x840, v10
	v_add_u32_e32 v54, 0x400, v10
	s_waitcnt vmcnt(6)
	ds_write2_b32 v10, v94, v95 offset1:66
	s_waitcnt vmcnt(4)
	ds_write2_b32 v10, v96, v97 offset0:132 offset1:198
	s_waitcnt vmcnt(2)
	ds_write2_b32 v54, v98, v99 offset0:8 offset1:74
	s_waitcnt vmcnt(0)
	ds_write2_b32 v54, v100, v101 offset0:140 offset1:206
	v_add_u32_e32 v10, 0x840, v10
	s_and_b32 s4, s30, 0x3fc0
	s_lshl_b32 s26, s38, 5
	s_addk_i32 s4, 0xe700
	s_and_b32 s28, s26, 0x7e0
	s_lshl_b64 s[26:27], s[22:23], 23
	s_add_u32 s23, s24, s26
	s_waitcnt lgkmcnt(0)
	s_addc_u32 s26, s25, s27
	s_lshl_b64 s[24:25], s[4:5], 1
	s_add_u32 s24, s23, s24
	ds_read2_b32 v[4:5], v25 offset0:33 offset1:41
	ds_read2_b32 v[6:7], v25 offset1:8
	ds_read2_b32 v[14:15], v25 offset0:66 offset1:74
	ds_read2_b32 v[16:17], v25 offset0:99 offset1:107
	ds_read2_b32 v[18:19], v25 offset0:132 offset1:140
	ds_read2_b32 v[20:21], v25 offset0:165 offset1:173
	ds_read2_b32 v[54:55], v25 offset0:198 offset1:206
	ds_read2_b32 v[56:57], v25 offset0:231 offset1:239
	s_addc_u32 s25, s26, s25
	v_lshlrev_b32_e32 v10, 1, v8
	v_lshl_add_u64 v[0:1], s[24:25], 0, v[10:11]
	v_lshl_add_u64 v[58:59], v[0:1], 0, s[18:19]
	s_waitcnt lgkmcnt(6)
	v_cvt_pk_bf16_f32 v0, v6, v4
	v_or_b32_e32 v4, s28, v24
	v_lshlrev_b32_e32 v10, 12, v4
	s_waitcnt lgkmcnt(4)
	v_cvt_pk_bf16_f32 v1, v14, v16
	s_waitcnt lgkmcnt(2)
	v_cvt_pk_bf16_f32 v2, v18, v20
	s_waitcnt lgkmcnt(0)
	v_cvt_pk_bf16_f32 v3, v54, v56
	v_lshl_add_u64 v[60:61], v[58:59], 0, v[10:11]
	global_store_dwordx4 v[60:61], v[0:3], off
	v_or_b32_e32 v4, s28, v26
	v_lshlrev_b32_e32 v10, 12, v4
	v_cvt_pk_bf16_f32 v0, v7, v5
	v_cvt_pk_bf16_f32 v1, v15, v17
	v_cvt_pk_bf16_f32 v2, v19, v21
	v_cvt_pk_bf16_f32 v3, v55, v57
	ds_read2_b32 v[6:7], v25 offset0:49 offset1:57
	ds_read2_b32 v[14:15], v25 offset0:16 offset1:24
	ds_read2_b32 v[16:17], v25 offset0:82 offset1:90
	ds_read2_b32 v[18:19], v25 offset0:115 offset1:123
	ds_read2_b32 v[20:21], v25 offset0:148 offset1:156
	ds_read2_b32 v[54:55], v25 offset0:181 offset1:189
	ds_read2_b32 v[56:57], v25 offset0:214 offset1:222
	ds_read2_b32 v[60:61], v25 offset0:247 offset1:255
	v_lshl_add_u64 v[4:5], v[58:59], 0, v[10:11]
	global_store_dwordx4 v[4:5], v[0:3], off
	v_or_b32_e32 v4, s28, v27
	v_lshlrev_b32_e32 v10, 12, v4
	s_waitcnt lgkmcnt(6)
	v_cvt_pk_bf16_f32 v0, v14, v6
	s_waitcnt lgkmcnt(4)
	v_cvt_pk_bf16_f32 v1, v16, v18
	s_waitcnt lgkmcnt(2)
	v_cvt_pk_bf16_f32 v2, v20, v54
	s_waitcnt lgkmcnt(0)
	v_cvt_pk_bf16_f32 v3, v56, v60
	v_lshl_add_u64 v[4:5], v[58:59], 0, v[10:11]
	global_store_dwordx4 v[4:5], v[0:3], off
	v_or_b32_e32 v4, s28, v28
	v_lshlrev_b32_e32 v10, 12, v4
	v_cvt_pk_bf16_f32 v0, v15, v7
	v_cvt_pk_bf16_f32 v1, v17, v19
	v_cvt_pk_bf16_f32 v2, v21, v55
	v_cvt_pk_bf16_f32 v3, v57, v61
	v_lshl_add_u64 v[4:5], v[58:59], 0, v[10:11]
	global_store_dwordx4 v[4:5], v[0:3], off
	s_waitcnt lgkmcnt(0)

; #define LAS __attribute__((address_space(3)))
; #define LDS_WAIT() asm volatile("s_waitcnt lgkmcnt(0)" ::: "memory")
; __device__ __forceinline__ void p0_transpose_item(const float* W, int K, int N, bfu* WT, int drow0, LAS float* scr, int k0, int n0, int lane, const float* gk) {
; #pragma unroll 8
;     for (int i = 0; i < 32; ++i) { const int kk = 2 * i + (lane >> 5); scr[kk * 33 + (lane & 31)] = __builtin_nontemporal_load(W + (size_t)(k0 + kk) * N + n0 + (lane & 31)); }
;     LDS_WAIT(); asm volatile("" ::: "memory");
;     const int c = lane & 7;
;     f32x4 ga = (f32x4){1.f, 1.f, 1.f, 1.f}, gb = ga;
;     if (gk) { ga = *(const f32x4*)(gk + k0 + 8 * c); gb = *(const f32x4*)(gk + k0 + 8 * c + 4); }
.LBB0_53:
	v_lshl_add_u64 v[54:55], v[20:21], 0, s[34:35]
	v_lshl_add_u64 v[56:57], v[18:19], 0, s[34:35]
	v_lshl_add_u64 v[58:59], v[16:17], 0, s[34:35]
	v_lshl_add_u64 v[60:61], v[14:15], 0, s[34:35]
	v_lshl_add_u64 v[62:63], v[6:7], 0, s[34:35]
	v_lshl_add_u64 v[64:65], v[4:5], 0, s[34:35]
	v_lshl_add_u64 v[66:67], v[2:3], 0, s[34:35]
	v_lshl_add_u64 v[68:69], v[0:1], 0, s[34:35]
	global_load_dword v70, v[54:55], off nt
	global_load_dword v71, v[56:57], off nt
	global_load_dword v72, v[58:59], off nt
	global_load_dword v73, v[60:61], off nt
	global_load_dword v74, v[62:63], off nt
	global_load_dword v75, v[64:65], off nt
	global_load_dword v76, v[66:67], off nt
	global_load_dword v77, v[68:69], off nt
	s_add_u32 s34, s34, 0x64000
	s_addc_u32 s35, s35, 0
	v_lshl_add_u64 v[54:55], v[20:21], 0, s[34:35]
	v_lshl_add_u64 v[56:57], v[18:19], 0, s[34:35]
	v_lshl_add_u64 v[58:59], v[16:17], 0, s[34:35]
	v_lshl_add_u64 v[60:61], v[14:15], 0, s[34:35]
	v_lshl_add_u64 v[62:63], v[6:7], 0, s[34:35]
	v_lshl_add_u64 v[64:65], v[4:5], 0, s[34:35]
	v_lshl_add_u64 v[66:67], v[2:3], 0, s[34:35]
	v_lshl_add_u64 v[68:69], v[0:1], 0, s[34:35]
	global_load_dword v78, v[54:55], off nt
	global_load_dword v79, v[56:57], off nt
	global_load_dword v80, v[58:59], off nt
	global_load_dword v81, v[60:61], off nt
	global_load_dword v82, v[62:63], off nt
	global_load_dword v83, v[64:65], off nt
	global_load_dword v84, v[66:67], off nt
	global_load_dword v85, v[68:69], off nt
	s_add_u32 s34, s34, 0x64000
	s_addc_u32 s35, s35, 0
	v_lshl_add_u64 v[54:55], v[20:21], 0, s[34:35]
	v_lshl_add_u64 v[56:57], v[18:19], 0, s[34:35]
	v_lshl_add_u64 v[58:59], v[16:17], 0, s[34:35]
	v_lshl_add_u64 v[60:61], v[14:15], 0, s[34:35]
	v_lshl_add_u64 v[62:63], v[6:7], 0, s[34:35]
	v_lshl_add_u64 v[64:65], v[4:5], 0, s[34:35]
	v_lshl_add_u64 v[66:67], v[2:3], 0, s[34:35]
	v_lshl_add_u64 v[68:69], v[0:1], 0, s[34:35]
	global_load_dword v86, v[54:55], off nt
	global_load_dword v87, v[56:57], off nt
	global_load_dword v88, v[58:59], off nt
	global_load_dword v89, v[60:61], off nt
	global_load_dword v90, v[62:63], off nt
	global_load_dword v91, v[64:65], off nt
	global_load_dword v92, v[66:67], off nt
	global_load_dword v93, v[68:69], off nt
	s_add_u32 s34, s34, 0x64000
	s_addc_u32 s35, s35, 0
	v_lshl_add_u64 v[54:55], v[20:21], 0, s[34:35]
	v_lshl_add_u64 v[56:57], v[18:19], 0, s[34:35]
	v_lshl_add_u64 v[58:59], v[16:17], 0, s[34:35]
	v_lshl_add_u64 v[60:61], v[14:15], 0, s[34:35]
	v_lshl_add_u64 v[62:63], v[6:7], 0, s[34:35]
	v_lshl_add_u64 v[64:65], v[4:5], 0, s[34:35]
	v_lshl_add_u64 v[66:67], v[2:3], 0, s[34:35]
	v_lshl_add_u64 v[68:69], v[0:1], 0, s[34:35]
	global_load_dword v94, v[54:55], off nt
	global_load_dword v95, v[56:57], off nt
	global_load_dword v96, v[58:59], off nt
	global_load_dword v97, v[60:61], off nt
	global_load_dword v98, v[62:63], off nt
	global_load_dword v99, v[64:65], off nt
	global_load_dword v100, v[66:67], off nt
	global_load_dword v101, v[68:69], off nt
	s_add_u32 s34, s34, 0x64000
	s_addc_u32 s35, s35, 0
	v_add_u32_e32 v54, 0x400, v10
	s_waitcnt vmcnt(30)
	ds_write2_b32 v10, v70, v71 offset1:66
	s_waitcnt vmcnt(28)
	ds_write2_b32 v10, v72, v73 offset0:132 offset1:198
	s_waitcnt vmcnt(26)
	ds_write2_b32 v54, v74, v75 offset0:8 offset1:74
	s_waitcnt vmcnt(24)
	ds_write2_b32 v54, v76, v77 offset0:140 offset1:206
	v_add_u32_e32 v10, 0x840, v10
	v_add_u32_e32 v54, 0x400, v10
	s_waitcnt vmcnt(22)
	ds_write2_b32 v10, v78, v79 offset1:66
	s_waitcnt vmcnt(20)
	ds_write2_b32 v10, v80, v81 offset0:132 offset1:198
	s_waitcnt vmcnt(18)
	ds_write2_b32 v54, v82, v83 offset0:8 offset1:74
	s_waitcnt vmcnt(16)
	ds_write2_b32 v54, v84, v85 offset0:140 offset1:206
	v_add_u32_e32 v10, 0x840, v10
	v_add_u32_e32 v54, 0x400, v10
	s_waitcnt vmcnt(14)
	ds_write2_b32 v10, v86, v87 offset1:66
	s_waitcnt vmcnt(12)
	ds_write2_b32 v10, v88, v89 offset0:132 offset1:198
	s_waitcnt vmcnt(10)
	ds_write2_b32 v54, v90, v91 offset0:8 offset1:74
	s_waitcnt vmcnt(8)
	ds_write2_b32 v54, v92, v93 offset0:140 offset1:206
	v_add_u32_e32 v10, 0x840, v10
	v_add_u32_e32 v54, 0x400, v10
	s_waitcnt vmcnt(6)
	ds_write2_b32 v10, v94, v95 offset1:66
	s_waitcnt vmcnt(4)
	ds_write2_b32 v10, v96, v97 offset0:132 offset1:198
	s_waitcnt vmcnt(2)
	ds_write2_b32 v54, v98, v99 offset0:8 offset1:74
	s_waitcnt vmcnt(0)
	ds_write2_b32 v54, v100, v101 offset0:140 offset1:206
	v_add_u32_e32 v10, 0x840, v10
	s_waitcnt lgkmcnt(0)
	s_waitcnt lgkmcnt(0)
	s_cmp_lg_u64 s[30:31], 0
	s_cbranch_scc0 .LBB0_56
	s_lshl_b32 s34, s22, 11
	s_ashr_i32 s35, s34, 31
	s_lshl_b64 s[34:35], s[34:35], 2
	s_add_u32 s4, s30, s34
	s_addc_u32 s23, s31, s35
	s_ashr_i32 s29, s28, 31
	s_lshl_b64 s[30:31], s[28:29], 2
	s_add_u32 s30, s4, s30
	s_addc_u32 s31, s23, s31
	v_lshlrev_b32_e32 v10, 2, v8
	global_load_dwordx4 v[0:3], v10, s[30:31] offset:16
	global_load_dwordx4 v[4:7], v10, s[30:31]
	s_cbranch_execnz .LBB0_21
	s_branch .LBB0_20
